# outer unit-loop heads of P1/P4/P5 also 64-byte aligned (on top of K-loop head alignment)
# speedup vs baseline: 1.0031x; 1.0031x over previous
;     __device__ __forceinline__ bool next(int i, Unit& u) const {
;     ...
;         int L = i * G + c;
;         if (L < 6144) { int pm, pn; remap_tile<4>(L, 128, 48, pm, pn); pn = (pn % 3) * 16 + pn / 3; u.pm = pm; u.pn = pn; u.kind = pn >> 4; u.A = U + (size_t)pm * TILE; u.B = Win + (size_t)pn * TILE; return true; }
.LBB0_106:
.LBB0_107:
	s_ashr_i32 s0, s2, 31
	s_lshr_b32 s0, s0, 29
	s_add_i32 s0, s2, s0
	s_and_b32 s1, s0, -8
	s_sub_i32 s1, s2, s1
	s_cmp_lt_i32 s1, 0
	s_movk_i32 s4, 0x301
	s_cselect_b32 s4, s4, 0x300
	s_mul_i32 s1, s4, s1
	s_ashr_i32 s0, s0, 3
	s_add_i32 s1, s1, s0
	s_mul_hi_i32 s0, s1, 0x2aaaaaab
	s_lshr_b32 s4, s0, 31
	s_ashr_i32 s0, s0, 5
	s_add_i32 s0, s0, s4
	s_lshl_b32 s4, s0, 2
	s_mulk_i32 s0, 0xc0
	s_sub_i32 s0, s1, s0
	s_sext_i32_i16 s1, s0
	s_bfe_u32 s1, s1, 0x2001d
	s_add_i32 s1, s0, s1
	s_sext_i32_i16 s5, s1
	s_and_b32 s1, s1, 0xfffc
	s_sub_i32 s0, s0, s1
	s_ashr_i32 s5, s5, 2
	s_sext_i32_i16 s0, s0
	s_add_i32 s96, s4, s0
	s_mul_i32 s0, s5, 0x56
	s_bfe_u32 s1, s0, 0x1000f
	s_bfe_u32 s0, s0, 0x80008
	s_add_i32 s0, s0, s1
	s_mul_i32 s1, s0, 3
	s_sub_i32 s1, s5, s1
	s_sext_i32_i8 s1, s1
	s_lshl_b32 s1, s1, 4
	s_sext_i32_i8 s0, s0
	s_add_i32 s90, s1, s0
	s_ashr_i32 s97, s96, 31
	s_ashr_i32 s13, s90, 4
	s_lshl_b64 s[0:1], s[96:97], 19
	s_add_u32 s4, s24, s0
	s_addc_u32 s5, s25, s1
	s_ashr_i32 s91, s90, 31
	s_lshl_b64 s[0:1], s[90:91], 19
	s_add_u32 s92, s26, s0
	s_addc_u32 s93, s27, s1
	s_mov_b64 s[0:1], -1
	.p2align	6

; #define GP_STAGE(bufoff, gbase, voff) do { _Pragma("unroll") for (int _i = 0; _i < 2; ++_i) \
;         __builtin_amdgcn_global_load_lds((const unsigned*)((const char*)(gbase) + (voff)[_i]), (LAS unsigned*)(lds + (bufoff) + ldsw + _i * 8192), 16, 0, 0); } while (0)
; #define GP_WAIT_V(n) asm volatile("s_waitcnt vmcnt(" #n ")" ::: "memory")
; #define GP_BAR __builtin_amdgcn_s_barrier()
; template <class Epi, class Sched>
; __device__ __forceinline__ void gemm_phase(LAS unsigned char* lds, const int lda, const int ldb, const int K, const Sched& S, const Epi& E, const int widx) {
;     ...
;     const int tid = tid_, wid = __builtin_amdgcn_readfirstlane(tid >> 6), lane = tid & 63, wr = wid >> 2, wc = wid & 3, fr = lane & 15, fq = lane >> 4;
;     const int nt = K / BK;
;     unsigned voffA[2], voffB[2];
; #pragma unroll
;     for (int i = 0; i < 2; ++i) { int R, C; stage_rc(tid * 16 + i * 8192, R, C); voffA[i] = (unsigned)(R * lda + C) * 2u; voffB[i] = (unsigned)(R * ldb + C) * 2u; }
;     const size_t kstep = (size_t)(BK * 2);
;     const size_t hstepA = (size_t)HALF * lda * 2, hstepB = (size_t)HALF * ldb * 2;
;     const unsigned ldsw = (unsigned)wid * 1024u;
;     const int aoff = lds_byte(wr * 64 + fr, fq * 8), boff = lds_byte(wc * 32 + fr, fq * 8);
;     ...
;     Unit cur, nxt; int ui = 0;
;     if (!S.next(0, cur)) return;
;     f32x4 acc[2][2][4][2];
; #pragma unroll
;     for (int a = 0; a < 2; ++a)
; #pragma unroll
;         for (int b = 0; b < 2; ++b)
; #pragma unroll
;             for (int m = 0; m < 4; ++m)
; #pragma unroll
;                 for (int n = 0; n < 2; ++n) acc[a][b][m][n] = (f32x4){0.f, 0.f, 0.f, 0.f};
;     bf16x8 At[4][2], B0[2][2], B1[2][2];
;     const char* cA = cur.A; const char* cB = cur.B;
;     GP_STAGE(GP_SB(0, 0), cB, voffB); GP_STAGE(GP_SB(0, 1), cB + hstepB, voffB); GP_STAGE(GP_SA(0, 0), cA, voffA); GP_STAGE(GP_SA(0, 1), cA + hstepA, voffA);
;     if (wr == 1) GP_BAR;
;     GP_WAIT_V(2); GP_BAR;
;     GP_STAGE(GP_SB(1, 0), cB + kstep, voffB); GP_STAGE(GP_SA(1, 0), cA + kstep, voffA); GP_STAGE(GP_SB(1, 1), cB + hstepB + kstep, voffB);
;     GP_WAIT_V(6); GP_BAR;
.LBB0_531:
	v_bfe_u32 v16, v8, 4, 2
	v_and_b32_e32 v15, 15, v8
	v_lshlrev_b32_e32 v17, 4, v16
	v_lshl_or_b32 v146, s30, 6, v15
	v_lshl_or_b32 v15, v15, 6, v17
	v_lshlrev_b32_e32 v17, 2, v8
	s_sext_i32_i8 s76, s4
	s_and_b32 s4, s8, 3
	s_lshl_b32 s8, s30, 13
	v_and_b32_e32 v17, 32, v17
	v_bitop3_b32 v18, v15, s8, v17 bitop3:0xde
	s_lshl_b32 s8, s4, 12
	v_bitop3_b32 v147, v15, s8, v17 bitop3:0xde
	s_mov_b64 s[8:9], 0x80
	s_add_i32 m0, s13, 0x18000
	v_lshl_add_u64 v[6:7], v[6:7], 0, s[8:9]
	s_lshl_b32 s38, s4, 5
	s_waitcnt vmcnt(2)
	s_barrier
	global_load_lds_dwordx4 v[6:7], off
	v_lshl_add_u64 v[4:5], v[4:5], 0, s[8:9]
	s_add_i32 m0, s13, 0x1a000
	s_add_i32 s71, s13, 0x8000
	s_add_i32 s72, s13, 0xa000
	global_load_lds_dwordx4 v[4:5], off
	v_lshl_add_u64 v[0:1], v[0:1], 0, s[8:9]
	s_mov_b32 m0, s71
	s_add_u32 s34, s66, 0x40080
	global_load_lds_dwordx4 v[0:1], off
	v_lshl_add_u64 v[0:1], v[2:3], 0, s[8:9]
	s_mov_b32 m0, s72
	s_addc_u32 s35, s67, 0
	global_load_lds_dwordx4 v[0:1], off
	s_add_i32 m0, s13, 0x1c000
	v_lshl_add_u64 v[0:1], s[34:35], 0, v[128:129]
	global_load_lds_dwordx4 v[0:1], off
	v_lshl_add_u64 v[0:1], s[34:35], 0, v[130:131]
	s_add_i32 m0, s13, 0x1e000
	s_cmpk_lt_u32 s10, 0x100
	global_load_lds_dwordx4 v[0:1], off
	v_lshlrev_b32_e32 v0, 14, v9
	v_and_b32_e32 v0, 0xffff8000, v0
	s_cselect_b64 s[10:11], -1, 0
	s_lshl_b32 s30, s30, 2
	v_lshl_add_u32 v0, v10, 11, v0
	v_and_b32_e32 v1, 1, v9
	s_or_b32 s30, s30, s4
	v_lshl_or_b32 v0, v1, 6, v0
	s_ashr_i32 s31, s30, 31
	v_lshl_add_u32 v136, v11, 1, v0
	v_lshlrev_b32_e32 v0, 14, v12
	s_lshl_b64 s[30:31], s[30:31], 14
	v_and_b32_e32 v0, 0xffff8000, v0
	v_and_b32_e32 v4, 63, v8
	s_add_u32 s20, s20, s30
	v_lshl_add_u32 v0, v13, 11, v0
	v_and_b32_e32 v1, 1, v12
	s_waitcnt vmcnt(6)
	v_lshlrev_b32_e32 v6, 2, v16
	s_addc_u32 s21, s21, s31
	v_lshlrev_b32_e32 v132, 3, v4
	v_lshl_or_b32 v0, v1, 6, v0
	v_mov_b32_e32 v2, v133
	v_mov_b32_e32 v3, v133
	v_lshl_add_u64 v[134:135], s[20:21], 0, v[132:133]
	v_lshl_add_u32 v138, v14, 1, v0
	v_mov_b32_e32 v0, v133
	v_mov_b32_e32 v1, v133
	v_add_u32_e32 v151, 0, v18
	v_lshlrev_b32_e32 v140, 1, v6
	v_lshlrev_b32_e32 v132, 3, v4
	v_mov_b64_e32 v[6:7], v[2:3]
	v_mov_b64_e32 v[10:11], v[2:3]
	v_mov_b64_e32 v[14:15], v[2:3]
	v_mov_b64_e32 v[18:19], v[2:3]
	v_mov_b64_e32 v[22:23], v[2:3]
	v_mov_b64_e32 v[26:27], v[2:3]
	v_mov_b64_e32 v[30:31], v[2:3]
	v_mov_b64_e32 v[34:35], v[2:3]
	v_mov_b64_e32 v[38:39], v[2:3]
	v_mov_b64_e32 v[42:43], v[2:3]
	v_mov_b64_e32 v[46:47], v[2:3]
	v_mov_b64_e32 v[50:51], v[2:3]
	v_mov_b64_e32 v[54:55], v[2:3]
	v_mov_b64_e32 v[58:59], v[2:3]
	v_mov_b64_e32 v[62:63], v[2:3]
	v_mov_b64_e32 v[66:67], v[2:3]
	v_mov_b64_e32 v[70:71], v[2:3]
	v_mov_b64_e32 v[74:75], v[2:3]
	v_mov_b64_e32 v[78:79], v[2:3]
	v_mov_b64_e32 v[82:83], v[2:3]
	v_mov_b64_e32 v[86:87], v[2:3]
	v_mov_b64_e32 v[90:91], v[2:3]
	v_mov_b64_e32 v[94:95], v[2:3]
	v_mov_b64_e32 v[98:99], v[2:3]
	v_mov_b64_e32 v[102:103], v[2:3]
	v_mov_b64_e32 v[106:107], v[2:3]
	v_mov_b64_e32 v[110:111], v[2:3]
	v_mov_b64_e32 v[114:115], v[2:3]
	v_mov_b64_e32 v[118:119], v[2:3]
	v_mov_b64_e32 v[122:123], v[2:3]
	v_mov_b64_e32 v[126:127], v[2:3]
	v_or_b32_e32 v148, 16, v146
	v_or_b32_e32 v149, 32, v146
	v_or_b32_e32 v150, 48, v146
	v_mov_b32_e32 v137, v133
	v_mov_b32_e32 v139, v133
	s_add_i32 s73, 0, 0x10000
	s_add_i32 s74, 0, 0x14000
	s_mov_b64 s[20:21], 0x800
	s_lshl_b32 s38, s38, 1
	s_mov_b64 s[42:43], 0x1000
	s_mov_b64 s[44:45], 0x1800
	s_mov_b64 s[46:47], 0x2000
	s_mov_b64 s[48:49], 0x2800
	s_mov_b64 s[50:51], 0x3000
	s_mov_b64 s[52:53], 0x3800
	v_mov_b64_e32 v[4:5], v[0:1]
	v_mov_b64_e32 v[8:9], v[0:1]
	v_mov_b64_e32 v[12:13], v[0:1]
	v_mov_b64_e32 v[16:17], v[0:1]
	v_mov_b64_e32 v[20:21], v[0:1]
	v_mov_b64_e32 v[24:25], v[0:1]
	v_mov_b64_e32 v[28:29], v[0:1]
	v_mov_b64_e32 v[32:33], v[0:1]
	v_mov_b64_e32 v[36:37], v[0:1]
	v_mov_b64_e32 v[40:41], v[0:1]
	v_mov_b64_e32 v[44:45], v[0:1]
	v_mov_b64_e32 v[48:49], v[0:1]
	v_mov_b64_e32 v[52:53], v[0:1]
	v_mov_b64_e32 v[56:57], v[0:1]
	v_mov_b64_e32 v[60:61], v[0:1]
	v_mov_b64_e32 v[64:65], v[0:1]
	v_mov_b64_e32 v[68:69], v[0:1]
	v_mov_b64_e32 v[72:73], v[0:1]
	v_mov_b64_e32 v[76:77], v[0:1]
	v_mov_b64_e32 v[80:81], v[0:1]
	v_mov_b64_e32 v[84:85], v[0:1]
	v_mov_b64_e32 v[88:89], v[0:1]
	v_mov_b64_e32 v[92:93], v[0:1]
	v_mov_b64_e32 v[96:97], v[0:1]
	v_mov_b64_e32 v[100:101], v[0:1]
	v_mov_b64_e32 v[104:105], v[0:1]
	v_mov_b64_e32 v[108:109], v[0:1]
	v_mov_b64_e32 v[112:113], v[0:1]
	v_mov_b64_e32 v[116:117], v[0:1]
	v_mov_b64_e32 v[120:121], v[0:1]
	v_mov_b64_e32 v[124:125], v[0:1]
	s_mov_b32 s68, s5
	s_mov_b32 s75, 0
	s_mov_b64 s[58:59], s[28:29]
	s_mov_b64 s[60:61], s[66:67]
	s_barrier
	s_branch .LBB0_534
	.p2align	6

; #define GP_STAGE(bufoff, gbase, voff) do { _Pragma("unroll") for (int _i = 0; _i < 2; ++_i) \
;         __builtin_amdgcn_global_load_lds((const unsigned*)((const char*)(gbase) + (voff)[_i]), (LAS unsigned*)(lds + (bufoff) + ldsw + _i * 8192), 16, 0, 0); } while (0)
; #define GP_WAIT_V(n) asm volatile("s_waitcnt vmcnt(" #n ")" ::: "memory")
; #define GP_BAR __builtin_amdgcn_s_barrier()
; template <class Epi, class Sched>
; __device__ __forceinline__ void gemm_phase(LAS unsigned char* lds, const int lda, const int ldb, const int K, const Sched& S, const Epi& E, const int widx) {
;     ...
;     const int tid = tid_, wid = __builtin_amdgcn_readfirstlane(tid >> 6), lane = tid & 63, wr = wid >> 2, wc = wid & 3, fr = lane & 15, fq = lane >> 4;
;     const int nt = K / BK;
;     unsigned voffA[2], voffB[2];
; #pragma unroll
;     for (int i = 0; i < 2; ++i) { int R, C; stage_rc(tid * 16 + i * 8192, R, C); voffA[i] = (unsigned)(R * lda + C) * 2u; voffB[i] = (unsigned)(R * ldb + C) * 2u; }
;     const size_t kstep = (size_t)(BK * 2);
;     const size_t hstepA = (size_t)HALF * lda * 2, hstepB = (size_t)HALF * ldb * 2;
;     const unsigned ldsw = (unsigned)wid * 1024u;
;     const int aoff = lds_byte(wr * 64 + fr, fq * 8), boff = lds_byte(wc * 32 + fr, fq * 8);
;     ...
;     Unit cur, nxt; int ui = 0;
;     if (!S.next(0, cur)) return;
;     f32x4 acc[2][2][4][2];
; #pragma unroll
;     for (int a = 0; a < 2; ++a)
; #pragma unroll
;         for (int b = 0; b < 2; ++b)
; #pragma unroll
;             for (int m = 0; m < 4; ++m)
; #pragma unroll
;                 for (int n = 0; n < 2; ++n) acc[a][b][m][n] = (f32x4){0.f, 0.f, 0.f, 0.f};
;     bf16x8 At[4][2], B0[2][2], B1[2][2];
;     const char* cA = cur.A; const char* cB = cur.B;
;     GP_STAGE(GP_SB(0, 0), cB, voffB); GP_STAGE(GP_SB(0, 1), cB + hstepB, voffB); GP_STAGE(GP_SA(0, 0), cA, voffA); GP_STAGE(GP_SA(0, 1), cA + hstepA, voffA);
;     if (wr == 1) GP_BAR;
;     GP_WAIT_V(2); GP_BAR;
;     GP_STAGE(GP_SB(1, 0), cB + kstep, voffB); GP_STAGE(GP_SA(1, 0), cA + kstep, voffA); GP_STAGE(GP_SB(1, 1), cB + hstepB + kstep, voffB);
;     GP_WAIT_V(6); GP_BAR;
.LBB0_619:
	s_mov_b64 s[8:9], 0x80
	s_and_b32 s20, s5, 3
	s_add_i32 m0, s13, 0x18000
	v_lshl_add_u64 v[6:7], v[6:7], 0, s[8:9]
	s_lshl_b32 s5, s4, 13
	s_lshl_b32 s11, s20, 12
	s_waitcnt vmcnt(2)
	s_barrier
	global_load_lds_dwordx4 v[6:7], off
	v_lshl_add_u64 v[4:5], v[4:5], 0, s[8:9]
	s_add_i32 m0, s13, 0x1a000
	s_add_i32 s47, s13, 0x8000
	s_add_i32 s48, s13, 0xa000
	global_load_lds_dwordx4 v[4:5], off
	v_lshl_add_u64 v[0:1], v[0:1], 0, s[8:9]
	s_mov_b32 m0, s47
	s_add_u32 s18, s42, 0x40080
	global_load_lds_dwordx4 v[0:1], off
	v_lshl_add_u64 v[0:1], v[2:3], 0, s[8:9]
	s_mov_b32 m0, s48
	s_addc_u32 s19, s43, 0
	global_load_lds_dwordx4 v[0:1], off
	s_add_i32 m0, s13, 0x1c000
	v_lshl_add_u64 v[0:1], s[18:19], 0, v[176:177]
	global_load_lds_dwordx4 v[0:1], off
	v_lshl_add_u64 v[0:1], s[18:19], 0, v[178:179]
	s_add_i32 m0, s13, 0x1e000
	v_lshlrev_b32_e32 v2, 2, v8
	global_load_lds_dwordx4 v[0:1], off
	v_bfe_u32 v1, v8, 4, 2
	v_and_b32_e32 v0, 15, v8
	v_lshlrev_b32_e32 v180, 4, v1
	v_lshl_or_b32 v183, s4, 6, v0
	v_lshl_or_b32 v0, v0, 6, v180
	v_and_b32_e32 v2, 32, v2
	s_cmpk_lt_u32 s10, 0x100
	v_bitop3_b32 v3, v0, s5, v2 bitop3:0xde
	v_bitop3_b32 v194, v0, s11, v2 bitop3:0xde
	s_cselect_b64 s[10:11], -1, 0
	s_lshl_b32 s4, s4, 2
	v_lshlrev_b32_e32 v0, 14, v9
	s_or_b32 s18, s4, s20
	v_and_b32_e32 v0, 0xffff8000, v0
	s_ashr_i32 s19, s18, 31
	v_cmp_eq_u32_e64 s[4:5], 0, v1
	v_lshl_add_u32 v0, v10, 11, v0
	v_and_b32_e32 v1, 1, v9
	s_lshl_b64 s[18:19], s[18:19], 14
	s_lshl_b32 s20, s20, 7
	v_lshl_or_b32 v0, v1, 6, v0
	s_add_u32 s20, s36, s20
	v_lshl_add_u32 v186, v11, 1, v0
	v_lshlrev_b32_e32 v0, 14, v12
	s_addc_u32 s21, s37, 0
	v_and_b32_e32 v0, 0xffff8000, v0
	s_waitcnt vmcnt(6)
	s_add_u32 s49, s90, s18
	v_lshl_add_u32 v0, v13, 11, v0
	v_and_b32_e32 v1, 1, v12
	s_addc_u32 s50, s91, s19
	v_lshl_or_b32 v0, v1, 6, v0
	s_add_i32 s51, 0, 0x10000
	s_add_i32 s52, 0, 0x14000
	v_and_b32_e32 v182, 63, v8
	v_or_b32_e32 v195, 16, v183
	v_or_b32_e32 v196, 32, v183
	v_or_b32_e32 v197, 48, v183
	v_lshl_add_u64 v[184:185], s[20:21], 0, v[180:181]
	v_mov_b32_e32 v187, v181
	v_lshl_add_u32 v188, v14, 1, v0
	v_mov_b32_e32 v189, v181
	v_add_u32_e32 v198, s51, v194
	v_add_u32_e32 v199, s52, v194
	v_add_u32_e32 v200, 0, v3
	v_mbcnt_hi_u32_b32 v201, -1, v252
	s_movk_i32 s53, 0x1000
	s_movk_i32 s54, 0x3000
	s_mov_b64 s[30:31], s[28:29]
	s_mov_b64 s[36:37], s[42:43]
	s_barrier
	s_branch .LBB0_622
	.p2align	6
